# grid barrier: followers invalidate only their vector L1; the XCD leader alone invalidates L2 after all local WGs arrived
# speedup vs baseline: 1.0165x; 1.0075x over previous
.LBB0_527:
	s_or_b64 exec, exec, s[2:3]
	v_cvt_f32_u32_e32 v4, v2
	s_waitcnt vmcnt(0)
	v_readfirstlane_b32 s2, v3
	v_sub_u32_e32 v3, 0, v2
	v_rcp_iflag_f32_e32 v4, v4
	v_add_u32_e32 v5, s2, v1
	v_mul_f32_e32 v4, 0x4f7ffffe, v4
	v_cvt_u32_f32_e32 v4, v4
	v_mul_lo_u32 v1, v3, v4
	v_mul_hi_u32 v1, v4, v1
	v_add_u32_e32 v1, v4, v1
	v_mul_hi_u32 v1, v5, v1
	v_mul_lo_u32 v3, v1, v2
	v_sub_u32_e32 v3, v5, v3
	v_add_u32_e32 v4, 1, v1
	v_cmp_ge_u32_e32 vcc, v3, v2
	s_nop 1
	v_cndmask_b32_e32 v1, v1, v4, vcc
	v_sub_u32_e32 v4, v3, v2
	v_cndmask_b32_e32 v3, v3, v4, vcc
	v_add_u32_e32 v4, 1, v1
	v_cmp_ge_u32_e32 vcc, v3, v2
	v_add_u32_e32 v3, 1, v5
	s_nop 0
	v_cndmask_b32_e32 v1, v1, v4, vcc
	v_mul_lo_u32 v4, v2, v1
	v_add_u32_e32 v2, v4, v2
	v_cmp_ne_u32_e32 vcc, v3, v2
	s_and_saveexec_b64 s[2:3], vcc
	s_xor_b64 s[2:3], exec, s[2:3]
	s_cbranch_execz .LBB0_541
	v_readlane_b32 s8, v254, 40
	v_readlane_b32 s9, v254, 41
	s_waitcnt lgkmcnt(0)
	s_nop 3
	buffer_inv sc0
	global_load_dword v0, v117, s[8:9] sc1
	s_waitcnt vmcnt(0)
	v_cmp_eq_u32_e32 vcc, v0, v1
	s_and_saveexec_b64 s[8:9], vcc
	s_cbranch_execz .LBB0_540
	s_mov_b32 s20, 1
	s_mov_b64 s[10:11], 0
	s_branch .LBB0_531
